# in-proj unit order: 32 consecutive WG ids = 2 row tiles x 16 column tiles, both layers
# baseline (speedup 1.0000x reference)
; __device__ __forceinline__ int opaque_tid(int wave_s) { return (wave_s << 6) | opaque_lane(); }
;     __host__ __device__ bool next(int i, Unit& u) const {
;     ...
;         int wgid = ex ? 0 : L; { const int q = nwg / NXCD, r = nwg % NXCD, xcd = wgid % NXCD, off = wgid / NXCD; wgid = (xcd < r ? xcd * (q + 1) : r * (q + 1) + (xcd - r) * q) + off; }
;         const int nig = WGM * nN, gid = wgid / nig, fm = gid * WGM, gsz = (nM - fm) < WGM ? (nM - fm) : WGM;
;         int pm_m = fm + ((wgid % nig) % gsz), pn_m = (wgid % nig) / gsz;
;         if (nN == 16 && G == 256) {
;             const int xcd = c & 7, j = c >> 3; pm_m = 8 * (2 * i + (xcd >> 2)) + (j & 7); pn_m = 4 * (xcd & 3) + (j >> 3); }
;         if (nN == 64 && G == 256) {
;             const int xcd = c & 7, j = c >> 3; pm_m = 4 * i + (j & 3); pn_m = 8 * xcd + (j >> 2); }
;         const int nk_e = nt / split;
;         u.pm = ex ? 96 : pm_m; u.pn = ex ? e / split : pn_m; u.nkt = ex ? nk_e : nt; u.kt0 = ex ? (e % split) * nk_e : 0;
; template <class Epi, class Sched, bool ALIGN_EPI = false, bool SP2 = false>
; __device__ __forceinline__ void gemm_phase(PG8_LAS unsigned char* lds, const Gemm g, const Sched& S, const Epi& E, int wave_s) {
;     const int tid = opaque_tid(wave_s), wid = __builtin_amdgcn_readfirstlane(tid >> 6), lane = tid & 63, wr = wid >> 2, wc = wid & 3, fr = lane & 15, fq = lane >> 4;
;     const int K = g.K;
;     unsigned voffA[2], voffB[2];
; #pragma unroll
;     for (int i = 0; i < 2; ++i) { int R, C; stage_rc(tid * 16 + i * 8192, R, C); const int Rb = Epi::PERM ? ((R & ~31) + perm32(R & 31)) : R;
;         voffA[i] = (unsigned)(R * K + C) * 2u; voffB[i] = (unsigned)(Rb * K + C) * 2u; }
;     const size_t kstep = (size_t)(BK * 2);
;     const size_t hstep = (size_t)HALF * K * 2;
;     const size_t tstep = 2 * hstep;
;     const unsigned ldsw = (unsigned)wid * 1024u;
;     const int aoff = lds_byte(wr * 64 + fr, fq * 8), boff = lds_byte(wc * 32 + fr, fq * 8);
;     ...
;     Unit cur, nxt; int ui = 0;
;     if (!S.next(0, cur)) return;
;     f32x4 acc[2][2][4][2];
; #pragma unroll
;     for (int a = 0; a < 2; ++a)
; #pragma unroll
;         for (int b = 0; b < 2; ++b)
; #pragma unroll
;             for (int m = 0; m < 4; ++m)
; #pragma unroll
;                 for (int n = 0; n < 2; ++n) acc[a][b][m][n] = (f32x4){0.f, 0.f, 0.f, 0.f};
;     bf16x8 At[4][2], B0[2][2], B1[2][2];
.LBB0_28:
	s_cmp_gt_i32 s68, 2
	s_cbranch_scc1 .LBB0_194
	s_load_dword s3, s[0:1], 0xac
	s_waitcnt lgkmcnt(0)
	s_cmp_lt_i32 s3, 3
	s_cbranch_scc1 .LBB0_194
	s_mov_b64 s[4:5], s[0:1]
	v_mbcnt_lo_u32_b32 v8, -1, 0
	v_mbcnt_hi_u32_b32 v8, -1, v8
	s_cmpk_gt_i32 s2, 0xf88
	v_or_b32_e32 v0, s92, v8
	s_nop 0
	v_readfirstlane_b32 s14, v0
	s_cbranch_scc1 .LBB0_136
	s_cmpk_lt_i32 s2, 0xf60
	s_cselect_b32 s6, s2, 0
	s_ashr_i32 s7, s6, 31
	s_lshr_b32 s7, s7, 29
	s_add_i32 s7, s6, s7
	s_ashr_i32 s8, s7, 3
	s_and_b32 s7, s7, -8
	s_sub_i32 s6, s6, s7
	s_cmp_lt_i32 s6, 0
	s_movk_i32 s33, 0x1ed
	s_cselect_b32 s7, s33, 0x1ec
	s_mul_i32 s6, s6, s7
	s_add_i32 s6, s6, s8
	v_lshlrev_b32_e32 v1, 4, v0
	s_mul_hi_u32 s7, s6, 0x31f3832
	s_mul_i32 s8, s7, 0x52
	s_sub_i32 s6, s6, s8
	s_lshl_b32 s7, s7, 1
	s_and_b32 s8, s6, 1
	s_add_i32 s7, s7, s8
	v_add_u32_e32 v2, 0x2000, v1
	v_ashrrev_i32_e32 v3, 31, v2
	v_lshrrev_b32_e32 v3, 22, v3
	v_add_u32_e32 v3, v2, v3
	v_ashrrev_i32_e32 v9, 10, v3
	v_mul_i32_i24_e32 v3, 0x400, v9
	v_sub_u32_e32 v2, v2, v3
	v_lshrrev_b32_e32 v3, 4, v2
	v_bitop3_b32 v2, v3, v2, 32 bitop3:0x6c
	v_ashrrev_i32_e32 v3, 31, v2
	v_lshrrev_b32_e32 v3, 26, v3
	s_cmpk_lt_i32 s2, 0xf60
	v_add_u32_e32 v3, v2, v3
	v_lshlrev_b32_e32 v4, 3, v9
	s_cselect_b32 s44, s7, 0x60
	s_load_dwordx2 s[18:19], s[4:5], 0xa0
	s_add_i32 s4, s2, 0xfffff0a0
	s_lshr_b32 s5, s6, 1
	v_ashrrev_i32_e32 v10, 6, v3
	v_and_b32_e32 v4, -16, v4
	s_cmpk_lt_i32 s2, 0xf60
	v_add_u32_e32 v4, v10, v4
	s_cselect_b32 s42, s5, s4
	v_and_b32_e32 v5, 3, v10
	s_mov_b32 s4, 0x7ffe0
	v_lshrrev_b32_e32 v6, 2, v4
	v_lshlrev_b32_e32 v7, 1, v4
	v_and_b32_e32 v3, 0xc0, v3
	v_and_or_b32 v5, v4, s4, v5
	v_and_b32_e32 v6, 4, v6
	v_and_b32_e32 v7, 24, v7
	v_sub_u32_e32 v2, v2, v3
	v_mov_b32_e32 v3, 1
	v_or3_b32 v5, v5, v6, v7
	v_lshlrev_b32_e32 v6, 5, v9
	v_ashrrev_i16_sdwa v2, v3, sext(v2) dst_sel:DWORD dst_unused:UNUSED_PAD src0_sel:DWORD src1_sel:BYTE_0
	v_and_b32_e32 v6, 32, v6
	v_bfe_i32 v11, v2, 0, 16
	v_add_lshl_u32 v2, v6, v11, 1
	v_lshl_add_u32 v128, v5, 13, v2
	v_lshl_add_u32 v130, v4, 13, v2
	v_bfe_i32 v2, v0, 27, 1
	v_lshrrev_b32_e32 v2, 22, v2
	v_add_u32_e32 v2, v1, v2
	v_and_b32_e32 v2, 0xfffffc00, v2
	v_sub_u32_e32 v1, v1, v2
	v_lshrrev_b32_e32 v2, 4, v1
	v_ashrrev_i32_e32 v4, 31, v0
	v_bitop3_b32 v1, v2, v1, 32 bitop3:0x6c
	v_lshrrev_b32_e32 v4, 26, v4
	v_ashrrev_i32_e32 v2, 31, v1
	v_add_u32_e32 v0, v0, v4
	s_waitcnt lgkmcnt(0)
	s_add_u32 s52, s18, 0x3b200000
	v_lshrrev_b32_e32 v2, 26, v2
	v_ashrrev_i32_e32 v13, 6, v0
	s_addc_u32 s53, s19, 0
	v_add_u32_e32 v2, v1, v2
	v_lshlrev_b32_e32 v0, 3, v13
	s_add_u32 s54, s18, 0x800000
	v_ashrrev_i32_e32 v12, 6, v2
	v_and_b32_e32 v0, -16, v0
	s_addc_u32 s55, s19, 0
	s_ashr_i32 s12, s14, 6
	v_add_u32_e32 v0, v12, v0
	v_and_b32_e32 v4, 3, v12
	s_ashr_i32 s45, s44, 31
	s_ashr_i32 s10, s14, 8
	s_lshl_b32 s56, s12, 10
	v_and_or_b32 v4, v0, s4, v4
	s_lshl_b64 s[4:5], s[44:45], 21
	v_lshrrev_b32_e32 v5, 2, v0
	v_lshlrev_b32_e32 v6, 1, v0
	v_and_b32_e32 v2, 0xc0, v2
	s_add_u32 s46, s52, s4
	v_and_b32_e32 v5, 4, v5
	v_and_b32_e32 v6, 24, v6
	v_sub_u32_e32 v1, v1, v2
	s_addc_u32 s47, s53, s5
	s_ashr_i32 s43, s42, 31
	v_or3_b32 v4, v4, v5, v6
	v_lshlrev_b32_e32 v5, 5, v13
	v_ashrrev_i16_sdwa v1, v3, sext(v1) dst_sel:DWORD dst_unused:UNUSED_PAD src0_sel:DWORD src1_sel:BYTE_0
	s_lshl_b64 s[4:5], s[42:43], 21
	v_and_b32_e32 v5, 32, v5
	v_bfe_i32 v14, v1, 0, 16
	s_add_u32 s48, s54, s4
	v_add_lshl_u32 v1, v5, v14, 1
	s_addc_u32 s49, s55, s5
	s_add_i32 s43, s56, 0
	v_lshl_add_u32 v132, v4, 13, v1
	s_add_i32 m0, s43, 0x10000
	v_lshl_add_u32 v134, v0, 13, v1
	global_load_lds_dwordx4 v132, s[48:49]
	s_add_i32 m0, s43, 0x12000
	s_add_u32 s4, s48, 0x100000
	global_load_lds_dwordx4 v128, s[48:49]
	s_addc_u32 s5, s49, 0
	s_add_i32 m0, s43, 0x14000
	s_add_i32 s57, s43, 0x2000
	global_load_lds_dwordx4 v132, s[4:5]
	s_add_i32 m0, s43, 0x16000
	s_load_dword s60, s[0:1], 0xb0
	global_load_lds_dwordx4 v128, s[4:5]
	s_mov_b32 m0, s43
	s_add_u32 s4, s46, 0x100000
	global_load_lds_dwordx4 v134, s[46:47]
	s_mov_b32 m0, s57
	s_addc_u32 s5, s47, 0
	s_add_i32 s58, s43, 0x4000
	global_load_lds_dwordx4 v130, s[46:47]
	s_mov_b32 m0, s58
	s_add_i32 s59, s43, 0x6000
	global_load_lds_dwordx4 v134, s[4:5]
	s_mov_b32 m0, s59
	v_mov_b32_e32 v133, 0
	global_load_lds_dwordx4 v130, s[4:5]
	v_mov_b32_e32 v129, v133
	v_mov_b32_e32 v135, v133
	v_mov_b32_e32 v131, v133
	s_cmp_eq_u32 s10, 1
	s_mov_b32 s31, 0
	v_lshl_add_u64 v[6:7], s[48:49], 0, v[132:133]
	v_lshl_add_u64 v[4:5], s[48:49], 0, v[128:129]
	v_lshl_add_u64 v[2:3], s[46:47], 0, v[134:135]
	v_lshl_add_u64 v[0:1], s[46:47], 0, v[130:131]
	s_cselect_b64 s[4:5], -1, 0
	s_cmp_lg_u32 s10, 1
	s_movk_i32 s61, 0x4000
	s_cbranch_scc1 .LBB0_33
	s_barrier

;     __host__ __device__ bool next(int i, Unit& u) const {
;         const int L = i * G + c;
;         if (L >= nwg + nN * split) return false;
;         const bool ex = L >= nwg;
;         const int e = ex ? L - nwg : 0;
;         int wgid = ex ? 0 : L; { const int q = nwg / NXCD, r = nwg % NXCD, xcd = wgid % NXCD, off = wgid / NXCD; wgid = (xcd < r ? xcd * (q + 1) : r * (q + 1) + (xcd - r) * q) + off; }
;         const int nig = WGM * nN, gid = wgid / nig, fm = gid * WGM, gsz = (nM - fm) < WGM ? (nM - fm) : WGM;
;         int pm_m = fm + ((wgid % nig) % gsz), pn_m = (wgid % nig) / gsz;
;         if (nN == 16 && G == 256) {
;             const int xcd = c & 7, j = c >> 3; pm_m = 8 * (2 * i + (xcd >> 2)) + (j & 7); pn_m = 4 * (xcd & 3) + (j >> 3); }
;         if (nN == 64 && G == 256) {
;             const int xcd = c & 7, j = c >> 3; pm_m = 4 * i + (j & 3); pn_m = 8 * xcd + (j >> 2); }
;         const int nk_e = nt / split;
;         u.pm = ex ? 96 : pm_m; u.pn = ex ? e / split : pn_m; u.nkt = ex ? nk_e : nt; u.kt0 = ex ? (e % split) * nk_e : 0;
.LBB0_36:
	s_add_i32 s71, s31, 1
	s_waitcnt lgkmcnt(0)
	s_mul_i32 s35, s71, s60
	s_add_i32 s35, s35, s2
	s_cmpk_lt_i32 s35, 0xf89
	s_cselect_b64 s[36:37], -1, 0
	s_cmpk_gt_i32 s35, 0xf88
	s_cbranch_scc1 .LBB0_38
	s_cmpk_lt_i32 s35, 0xf60
	s_cselect_b32 s30, s35, 0
	s_ashr_i32 s34, s30, 31
	s_lshr_b32 s34, s34, 29
	s_add_i32 s34, s30, s34
	s_ashr_i32 s38, s34, 3
	s_and_b32 s34, s34, -8
	s_sub_i32 s30, s30, s34
	s_cmp_lt_i32 s30, 0
	s_cselect_b32 s34, s33, 0x1ec
	s_mul_i32 s30, s30, s34
	s_add_i32 s30, s30, s38
	s_mul_hi_u32 s34, s30, 0x31f3832
	s_lshl_b32 s40, s34, 1
	s_mulk_i32 s34, 0x52
	s_sub_i32 s30, s30, s34
	s_lshr_b32 s34, s30, 1
	s_and_b32 s30, s30, 1
	s_add_i32 s40, s40, s30
	s_cmpk_lt_i32 s35, 0xf60
	s_cselect_b32 s30, s40, 0x60
	s_add_i32 s38, s35, 0xfffff0a0
	s_cmpk_lt_i32 s35, 0xf60
	s_sext_i32_i16 s34, s34
	s_cselect_b32 s34, s34, s38

; __device__ __forceinline__ int opaque_tid(int wave_s) { return (wave_s << 6) | opaque_lane(); }
;     __host__ __device__ bool next(int i, Unit& u) const {
;     ...
;         int wgid = ex ? 0 : L; { const int q = nwg / NXCD, r = nwg % NXCD, xcd = wgid % NXCD, off = wgid / NXCD; wgid = (xcd < r ? xcd * (q + 1) : r * (q + 1) + (xcd - r) * q) + off; }
;         const int nig = WGM * nN, gid = wgid / nig, fm = gid * WGM, gsz = (nM - fm) < WGM ? (nM - fm) : WGM;
;         int pm_m = fm + ((wgid % nig) % gsz), pn_m = (wgid % nig) / gsz;
;         if (nN == 16 && G == 256) {
;             const int xcd = c & 7, j = c >> 3; pm_m = 8 * (2 * i + (xcd >> 2)) + (j & 7); pn_m = 4 * (xcd & 3) + (j >> 3); }
;         if (nN == 64 && G == 256) {
;             const int xcd = c & 7, j = c >> 3; pm_m = 4 * i + (j & 3); pn_m = 8 * xcd + (j >> 2); }
;         const int nk_e = nt / split;
;         u.pm = ex ? 96 : pm_m; u.pn = ex ? e / split : pn_m; u.nkt = ex ? nk_e : nt; u.kt0 = ex ? (e % split) * nk_e : 0;
; template <class Epi, class Sched, bool ALIGN_EPI = false, bool SP2 = false>
; __device__ __forceinline__ void gemm_phase(PG8_LAS unsigned char* lds, const Gemm g, const Sched& S, const Epi& E, int wave_s) {
;     const int tid = opaque_tid(wave_s), wid = __builtin_amdgcn_readfirstlane(tid >> 6), lane = tid & 63, wr = wid >> 2, wc = wid & 3, fr = lane & 15, fq = lane >> 4;
;     const int K = g.K;
;     unsigned voffA[2], voffB[2];
; #pragma unroll
;     for (int i = 0; i < 2; ++i) { int R, C; stage_rc(tid * 16 + i * 8192, R, C); const int Rb = Epi::PERM ? ((R & ~31) + perm32(R & 31)) : R;
;         voffA[i] = (unsigned)(R * K + C) * 2u; voffB[i] = (unsigned)(Rb * K + C) * 2u; }
;     const size_t kstep = (size_t)(BK * 2);
;     const size_t hstep = (size_t)HALF * K * 2;
;     const size_t tstep = 2 * hstep;
;     const unsigned ldsw = (unsigned)wid * 1024u;
;     const int aoff = lds_byte(wr * 64 + fr, fq * 8), boff = lds_byte(wc * 32 + fr, fq * 8);
;     ...
;     Unit cur, nxt; int ui = 0;
;     if (!S.next(0, cur)) return;
;     f32x4 acc[2][2][4][2];
; #pragma unroll
;     for (int a = 0; a < 2; ++a)
; #pragma unroll
;         for (int b = 0; b < 2; ++b)
; #pragma unroll
;             for (int m = 0; m < 4; ++m)
; #pragma unroll
;                 for (int n = 0; n < 2; ++n) acc[a][b][m][n] = (f32x4){0.f, 0.f, 0.f, 0.f};
;     bf16x8 At[4][2], B0[2][2], B1[2][2];
.LBB0_1540:
	s_cmp_gt_i32 s68, 12
	s_cbranch_scc1 .LBB0_1607
	s_load_dword s3, s[0:1], 0xac
	s_waitcnt lgkmcnt(0)
	s_cmp_lt_i32 s3, 13
	s_cbranch_scc1 .LBB0_1607
	s_mov_b64 s[4:5], s[0:1]
	v_mbcnt_lo_u32_b32 v8, -1, 0
	v_mbcnt_hi_u32_b32 v8, -1, v8
	s_cmpk_gt_i32 s2, 0xf88
	v_or_b32_e32 v0, s92, v8
	s_nop 0
	v_readfirstlane_b32 s14, v0
	s_cbranch_scc1 .LBB0_1566
	s_cmpk_lt_i32 s2, 0xf60
	s_cselect_b32 s6, s2, 0
	s_ashr_i32 s7, s6, 31
	s_lshr_b32 s7, s7, 29
	s_add_i32 s7, s6, s7
	s_ashr_i32 s8, s7, 3
	s_and_b32 s7, s7, -8
	s_sub_i32 s6, s6, s7
	s_cmp_lt_i32 s6, 0
	s_movk_i32 s33, 0x1ed
	s_cselect_b32 s7, s33, 0x1ec
	s_mul_i32 s6, s6, s7
	s_add_i32 s6, s6, s8
	v_lshlrev_b32_e32 v1, 4, v0
	s_mul_hi_u32 s7, s6, 0x31f3832
	s_mul_i32 s8, s7, 0x52
	s_sub_i32 s6, s6, s8
	s_lshl_b32 s7, s7, 1
	s_and_b32 s8, s6, 1
	s_add_i32 s7, s7, s8
	v_add_u32_e32 v2, 0x2000, v1
	v_ashrrev_i32_e32 v3, 31, v2
	v_lshrrev_b32_e32 v3, 22, v3
	v_add_u32_e32 v3, v2, v3
	v_ashrrev_i32_e32 v9, 10, v3
	v_mul_i32_i24_e32 v3, 0x400, v9
	v_sub_u32_e32 v2, v2, v3
	v_lshrrev_b32_e32 v3, 4, v2
	v_bitop3_b32 v2, v3, v2, 32 bitop3:0x6c
	v_ashrrev_i32_e32 v3, 31, v2
	v_lshrrev_b32_e32 v3, 26, v3
	s_cmpk_lt_i32 s2, 0xf60
	v_add_u32_e32 v3, v2, v3
	v_lshlrev_b32_e32 v4, 3, v9
	s_cselect_b32 s44, s7, 0x60
	s_load_dwordx2 s[18:19], s[4:5], 0xa0
	s_add_i32 s4, s2, 0xfffff0a0
	s_lshr_b32 s5, s6, 1
	v_ashrrev_i32_e32 v10, 6, v3
	v_and_b32_e32 v4, -16, v4
	s_cmpk_lt_i32 s2, 0xf60
	v_add_u32_e32 v4, v10, v4
	s_cselect_b32 s42, s5, s4
	v_and_b32_e32 v5, 3, v10
	s_mov_b32 s4, 0x7ffe0
	v_lshrrev_b32_e32 v6, 2, v4
	v_lshlrev_b32_e32 v7, 1, v4
	v_and_b32_e32 v3, 0xc0, v3
	v_and_or_b32 v5, v4, s4, v5
	v_and_b32_e32 v6, 4, v6
	v_and_b32_e32 v7, 24, v7
	v_sub_u32_e32 v2, v2, v3
	v_mov_b32_e32 v3, 1
	v_or3_b32 v5, v5, v6, v7
	v_lshlrev_b32_e32 v6, 5, v9
	v_ashrrev_i16_sdwa v2, v3, sext(v2) dst_sel:DWORD dst_unused:UNUSED_PAD src0_sel:DWORD src1_sel:BYTE_0
	v_and_b32_e32 v6, 32, v6
	v_bfe_i32 v11, v2, 0, 16
	v_add_lshl_u32 v2, v6, v11, 1
	v_lshl_add_u32 v128, v5, 13, v2
	v_lshl_add_u32 v130, v4, 13, v2
	v_bfe_i32 v2, v0, 27, 1
	v_lshrrev_b32_e32 v2, 22, v2
	v_add_u32_e32 v2, v1, v2
	v_and_b32_e32 v2, 0xfffffc00, v2
	v_sub_u32_e32 v1, v1, v2
	v_lshrrev_b32_e32 v2, 4, v1
	v_ashrrev_i32_e32 v4, 31, v0
	v_bitop3_b32 v1, v2, v1, 32 bitop3:0x6c
	v_lshrrev_b32_e32 v4, 26, v4
	v_ashrrev_i32_e32 v2, 31, v1
	v_add_u32_e32 v0, v0, v4
	s_waitcnt lgkmcnt(0)
	s_add_u32 s52, s18, 0x3b200000
	v_lshrrev_b32_e32 v2, 26, v2
	s_waitcnt vmcnt(0)
	v_ashrrev_i32_e32 v13, 6, v0
	s_addc_u32 s53, s19, 0
	v_add_u32_e32 v2, v1, v2
	v_lshlrev_b32_e32 v0, 3, v13
	s_add_u32 s54, s18, 0x5a00000
	v_ashrrev_i32_e32 v12, 6, v2
	v_and_b32_e32 v0, -16, v0
	s_addc_u32 s55, s19, 0
	s_ashr_i32 s12, s14, 6
	v_add_u32_e32 v0, v12, v0
	v_and_b32_e32 v4, 3, v12
	s_ashr_i32 s45, s44, 31
	s_ashr_i32 s10, s14, 8
	s_lshl_b32 s56, s12, 10
	v_and_or_b32 v4, v0, s4, v4
	s_lshl_b64 s[4:5], s[44:45], 21
	v_lshrrev_b32_e32 v5, 2, v0
	v_lshlrev_b32_e32 v6, 1, v0
	v_and_b32_e32 v2, 0xc0, v2
	s_add_u32 s46, s52, s4
	v_and_b32_e32 v5, 4, v5
	v_and_b32_e32 v6, 24, v6
	v_sub_u32_e32 v1, v1, v2
	s_addc_u32 s47, s53, s5
	s_ashr_i32 s43, s42, 31
	v_or3_b32 v4, v4, v5, v6
	v_lshlrev_b32_e32 v5, 5, v13
	v_ashrrev_i16_sdwa v1, v3, sext(v1) dst_sel:DWORD dst_unused:UNUSED_PAD src0_sel:DWORD src1_sel:BYTE_0
	s_lshl_b64 s[4:5], s[42:43], 21
	v_and_b32_e32 v5, 32, v5
	v_bfe_i32 v14, v1, 0, 16
	s_add_u32 s48, s54, s4
	v_add_lshl_u32 v1, v5, v14, 1
	s_addc_u32 s49, s55, s5
	s_add_i32 s43, s56, 0
	v_lshl_add_u32 v132, v4, 13, v1
	s_add_i32 m0, s43, 0x10000
	v_lshl_add_u32 v134, v0, 13, v1
	global_load_lds_dwordx4 v132, s[48:49]
	s_add_i32 m0, s43, 0x12000
	s_add_u32 s4, s48, 0x100000
	global_load_lds_dwordx4 v128, s[48:49]
	s_addc_u32 s5, s49, 0
	s_add_i32 m0, s43, 0x14000
	s_add_i32 s57, s43, 0x2000
	global_load_lds_dwordx4 v132, s[4:5]
	s_add_i32 m0, s43, 0x16000
	s_load_dword s60, s[0:1], 0xb0
	global_load_lds_dwordx4 v128, s[4:5]
	s_mov_b32 m0, s43
	s_add_u32 s4, s46, 0x100000
	global_load_lds_dwordx4 v134, s[46:47]
	s_mov_b32 m0, s57
	s_addc_u32 s5, s47, 0
	s_add_i32 s58, s43, 0x4000
	global_load_lds_dwordx4 v130, s[46:47]
	s_mov_b32 m0, s58
	s_add_i32 s59, s43, 0x6000
	global_load_lds_dwordx4 v134, s[4:5]
	s_mov_b32 m0, s59
	v_mov_b32_e32 v133, 0
	global_load_lds_dwordx4 v130, s[4:5]
	v_mov_b32_e32 v129, v133
	v_mov_b32_e32 v135, v133
	v_mov_b32_e32 v131, v133
	s_cmp_eq_u32 s10, 1
	s_mov_b32 s31, 0
	v_lshl_add_u64 v[6:7], s[48:49], 0, v[132:133]
	v_lshl_add_u64 v[4:5], s[48:49], 0, v[128:129]
	v_lshl_add_u64 v[2:3], s[46:47], 0, v[134:135]
	v_lshl_add_u64 v[0:1], s[46:47], 0, v[130:131]
	s_cselect_b64 s[4:5], -1, 0
	s_cmp_lg_u32 s10, 1
	s_movk_i32 s61, 0x4000
	s_cbranch_scc1 .LBB0_1545
	s_barrier
